# P8: per-unit next-tile index arithmetic (scalar division etc.) moved from the gap between units into the MFMA shadow of the peeled first k-iteration
# baseline (speedup 1.0000x reference)
; __device__ __forceinline__ int xcd_remap(int L, int nwg) { const int q = nwg / NXCD, r = nwg % NXCD, xcd = L % NXCD, off = L / NXCD; return (xcd < r ? xcd * (q + 1) : r * (q + 1) + (xcd - r) * q) + off; }
; #define PG8_STAGE(bufoff, gbase, voff) do { _Pragma("unroll") for (int _i = 0; _i < 2; ++_i) \
;         __builtin_amdgcn_global_load_lds((const unsigned*)((const char*)(gbase) + (voff)[_i]), (PG8_LAS unsigned*)(lds + (bufoff) + ldsw + _i * 8192), 16, 0, 0); } while (0)
; #define PG8_LDA(dst, b, h) do { _Pragma("unroll") for (int m = 0; m < 4; ++m) _Pragma("unroll") for (int k = 0; k < 2; ++k) dst[m][k] = *(const PG8_LAS bf16x8*)(lds + PG8_SA(b, h) + aoff + m * 2048 + k * 1024); } while (0)
; #define PG8_WAIT_V(n) asm volatile("s_waitcnt vmcnt(" #n ")" ::: "memory")
;     __device__ bool next(int i, Unit& u) const {
;         const long L = (long)i * G + c; if (L >= nwg) return false;
;         const int wgid = xcd_remap((int)L, nwg);
;         const int nig = WGM * nN, gid = wgid / nig, fm = gid * WGM, gsz = (nM - fm) < WGM ? (nM - fm) : WGM;
;         int pm = fm + ((wgid % nig) % gsz); const int pn = (wgid % nig) / gsz;
;         if (perm) { const int x = pm >> 4, j = pm & 15; pm = (j < 8) ? 8 * x + j : 64 + 8 * x + (j - 8); } u.aoff = (size_t)pm * atile; u.boff = (size_t)pn * btile + (size_t)(pm >> 3) * bbatch; u.r0 = pm * BM; u.c0 = pn * BM; u.sel = 0; return true;
; template <class Epi, class Sched>
; __device__ __forceinline__ void gemm_phase(PG8_LAS unsigned char* lds, PG8_LAS unsigned char* xl, const Gemm g, const Sched& S, const Epi& E) {
;     ...
;         const bool has_next = S.next(ui + 1, nxt);
;         const char* nA = has_next ? (const char*)g.A + nxt.aoff : cA; const char* nB = has_next ? (const char*)g.Bt + nxt.boff : cB;
; #pragma unroll 1
;         for (int t = 0; t < nt; t += 2) {
;             const bool last = (t == nt - 2);
;             const char* a1 = cA + (size_t)(t + 1) * kstep;
;             const char* a2 = last ? nA : cA + (size_t)(t + 2) * kstep; const char* b2 = last ? nB : cB + (size_t)(t + 2) * kstep;
;             const char* a3 = a2 + kstep; const char* b3 = b2 + kstep;
;             PG8_LDB(B0, 0, 0); PG8_LDB(B1, 0, 1); PG8_SCHED; PG8_LDA(At, 0, 0); PG8_STAGE(PG8_SA(1, 1), a1 + hsA, voffA);
;             PG8_WAIT_V(8); PG8_WAIT_L(0); PG8_BAR; PG8_MMA(0, 0, At, B0); PG8_MMA(0, 1, At, B1); PG8_BAR; PG8_SCHED;
.LBB0_822:
.LBB0_824:
	s_add_u32 s73, s2, 0x100
	s_addc_u32 s74, s3, 0
	s_add_u32 s2, s30, 0x40080
	v_mov_b32_e32 v0, 0
	s_addc_u32 s3, s31, 0
	s_mov_b32 s75, -2
	ds_read_b128 v[170:173], v164
	ds_read_b128 v[174:177], v164 offset:1024
	ds_read_b128 v[180:183], v164 offset:2048
	ds_read_b128 v[184:187], v164 offset:3072
	ds_read_b128 v[188:191], v165
	ds_read_b128 v[192:195], v165 offset:1024
	ds_read_b128 v[196:199], v165 offset:2048
	ds_read_b128 v[200:203], v165 offset:3072
	s_add_u32 s30, s2, 0xfffc0080
	s_addc_u32 s31, s3, -1
	s_cmp_eq_u32 s75, 12
	s_cselect_b32 s35, s46, s31
	s_cselect_b32 s34, s47, s30
	s_cselect_b32 s31, s70, s74
	s_cselect_b32 s30, s72, s73
	v_lshl_add_u64 v[238:239], s[2:3], 0, v[140:141]
	s_add_i32 m0, s55, 0xc000
	ds_read_b128 v[204:207], v166
	ds_read_b128 v[208:211], v166 offset:1024
	ds_read_b128 v[212:215], v166 offset:2048
	ds_read_b128 v[216:219], v166 offset:3072
	ds_read_b128 v[222:225], v166 offset:4096
	ds_read_b128 v[226:229], v166 offset:5120
	ds_read_b128 v[230:233], v166 offset:6144
	ds_read_b128 v[234:237], v166 offset:7168
	global_load_lds_dwordx4 v[238:239], off
	v_lshl_add_u64 v[238:239], s[2:3], 0, v[138:139]
	s_add_i32 m0, s55, 0xe000
	s_nop 0
	global_load_lds_dwordx4 v[238:239], off
	s_waitcnt vmcnt(8)
	s_waitcnt lgkmcnt(0)
	s_barrier
	s_setprio 1
	s_waitcnt lgkmcnt(0)
	v_mfma_f32_16x16x32_bf16 v[124:127], v[170:173], v[204:207], 0
	s_add_i32 s65, s65, 1
	s_mul_i32 s6, s65, s71
	s_mul_hi_u32 s7, s65, s40
	v_mfma_f32_16x16x32_bf16 v[116:119], v[180:183], v[204:207], 0
	s_add_i32 s7, s7, s6
	s_mul_i32 s6, s65, s40
	s_add_u32 s26, s6, s36
	v_mfma_f32_16x16x32_bf16 v[108:111], v[170:173], v[212:215], 0
	s_addc_u32 s27, s7, s52
	v_cmp_lt_i64_e64 s[6:7], s[26:27], v[142:143]
	s_ashr_i32 s20, s26, 31
	v_mfma_f32_16x16x32_bf16 v[100:103], v[180:183], v[212:215], 0
	s_lshr_b32 s20, s20, 29
	s_add_i32 s20, s26, s20
	s_ashr_i32 s21, s20, 3
	v_mfma_f32_16x16x32_bf16 v[92:95], v[170:173], v[222:225], 0
	s_and_b32 s20, s20, -8
	s_sub_i32 s20, s26, s20
	s_cmp_lt_i32 s20, 0
	v_mfma_f32_16x16x32_bf16 v[84:87], v[180:183], v[222:225], 0
	s_cselect_b32 s22, s53, 0x160
	s_mul_i32 s20, s20, s22
	s_add_i32 s20, s20, s21
	v_mfma_f32_16x16x32_bf16 v[76:79], v[170:173], v[230:233], 0
	s_mul_hi_i32 s21, s20, 0x2e8ba2e9
	s_lshr_b32 s22, s21, 31
	s_ashr_i32 s21, s21, 5
	v_mfma_f32_16x16x32_bf16 v[68:71], v[180:183], v[230:233], 0
	s_add_i32 s21, s21, s22
	s_lshl_b32 s22, s21, 3
	s_sub_i32 s23, 0x80, s22
	v_mfma_f32_16x16x32_bf16 v[124:127], v[174:177], v[208:211], v[124:127]
	s_min_i32 s23, s23, 8
	s_abs_i32 s26, s23
	v_cvt_f32_u32_e32 v254, s26
	v_mfma_f32_16x16x32_bf16 v[116:119], v[184:187], v[208:211], v[116:119]
	s_sub_i32 s28, 0, s26
	s_mulk_i32 s21, 0xb0
	s_sub_i32 s20, s20, s21
	v_mfma_f32_16x16x32_bf16 v[108:111], v[174:177], v[216:219], v[108:111]
	v_rcp_iflag_f32_e32 v254, v254
	s_abs_i32 s21, s20
	s_xor_b32 s27, s20, s23
	v_mfma_f32_16x16x32_bf16 v[100:103], v[184:187], v[216:219], v[100:103]
	s_ashr_i32 s27, s27, 31
	v_mul_f32_e32 v254, 0x4f7ffffe, v254
	v_cvt_u32_f32_e32 v254, v254
	v_mfma_f32_16x16x32_bf16 v[92:95], v[174:177], v[226:229], v[92:95]
	s_nop 0
	v_readfirstlane_b32 s29, v254
	s_mul_i32 s28, s28, s29
	v_mfma_f32_16x16x32_bf16 v[84:87], v[184:187], v[226:229], v[84:87]
	s_mul_hi_u32 s28, s29, s28
	s_add_i32 s29, s29, s28
	s_mul_hi_u32 s28, s21, s29
	v_mfma_f32_16x16x32_bf16 v[76:79], v[174:177], v[234:237], v[76:79]
	s_mul_i32 s29, s28, s26
	s_sub_i32 s21, s21, s29
	s_add_i32 s100, s28, 1
	v_mfma_f32_16x16x32_bf16 v[68:71], v[184:187], v[234:237], v[68:71]
	s_sub_i32 s29, s21, s26
	s_cmp_ge_u32 s21, s26
	s_cselect_b32 s28, s100, s28
	s_setprio 0
	s_setprio 1
	v_mfma_f32_16x16x32_bf16 v[120:123], v[188:191], v[204:207], 0
	s_cselect_b32 s21, s29, s21
	s_add_i32 s29, s28, 1
	s_cmp_ge_u32 s21, s26
	v_mfma_f32_16x16x32_bf16 v[112:115], v[196:199], v[204:207], 0
	s_cselect_b32 s21, s29, s28
	s_xor_b32 s21, s21, s27
	s_sub_i32 s26, s21, s27
	v_mfma_f32_16x16x32_bf16 v[104:107], v[188:191], v[212:215], 0
	s_mul_i32 s21, s26, s23
	s_sub_i32 s20, s20, s21
	s_add_i32 s28, s22, s20
	v_mfma_f32_16x16x32_bf16 v[96:99], v[196:199], v[212:215], 0
	s_ashr_i32 s29, s28, 31
	s_ashr_i32 s27, s26, 31
	s_lshl_b64 s[20:21], s[28:29], 19
	v_mfma_f32_16x16x32_bf16 v[88:91], v[188:191], v[222:225], 0
	s_lshl_b64 s[22:23], s[26:27], 19
	s_lshl_b32 s67, s28, 8
	s_lshl_b32 s66, s26, 8
	v_mfma_f32_16x16x32_bf16 v[80:83], v[196:199], v[222:225], 0
	s_add_u32 s26, s37, s20
	s_addc_u32 s27, s42, s21
	s_and_b64 s[28:29], s[6:7], exec
	v_mfma_f32_16x16x32_bf16 v[72:75], v[188:191], v[230:233], 0
	s_cselect_b32 s46, s27, s42
	s_cselect_b32 s47, s26, s37
	s_add_u32 s28, s43, s22
	v_mfma_f32_16x16x32_bf16 v[64:67], v[196:199], v[230:233], 0
	s_addc_u32 s29, s50, s23
	s_and_b64 s[100:101], s[6:7], exec
	s_cselect_b32 s70, s29, s50
	v_mfma_f32_16x16x32_bf16 v[120:123], v[192:195], v[208:211], v[120:123]
	s_cselect_b32 s72, s28, s43
	v_mfma_f32_16x16x32_bf16 v[112:115], v[200:203], v[208:211], v[112:115]
	v_mfma_f32_16x16x32_bf16 v[104:107], v[192:195], v[216:219], v[104:107]
	v_mfma_f32_16x16x32_bf16 v[96:99], v[200:203], v[216:219], v[96:99]
	v_mfma_f32_16x16x32_bf16 v[88:91], v[192:195], v[226:229], v[88:91]
	v_mfma_f32_16x16x32_bf16 v[80:83], v[200:203], v[226:229], v[80:83]
	v_mfma_f32_16x16x32_bf16 v[72:75], v[192:195], v[234:237], v[72:75]
	v_mfma_f32_16x16x32_bf16 v[64:67], v[200:203], v[234:237], v[64:67]
	s_setprio 0
	s_barrier
; #define PG8_STAGE(bufoff, gbase, voff) do { _Pragma("unroll") for (int _i = 0; _i < 2; ++_i) \
;         __builtin_amdgcn_global_load_lds((const unsigned*)((const char*)(gbase) + (voff)[_i]), (PG8_LAS unsigned*)(lds + (bufoff) + ldsw + _i * 8192), 16, 0, 0); } while (0)
; #define PG8_LDA(dst, b, h) do { _Pragma("unroll") for (int m = 0; m < 4; ++m) _Pragma("unroll") for (int k = 0; k < 2; ++k) dst[m][k] = *(const PG8_LAS bf16x8*)(lds + PG8_SA(b, h) + aoff + m * 2048 + k * 1024); } while (0)
; #define PG8_LDB(dst, b, h) do { _Pragma("unroll") for (int n = 0; n < 2; ++n) _Pragma("unroll") for (int k = 0; k < 2; ++k) dst[n][k] = *(const PG8_LAS bf16x8*)(lds + PG8_SB(b, h) + boff + n * 2048 + k * 1024); } while (0)
; #define PG8_MMA(ai, bj, At, Bt) do { __builtin_amdgcn_s_setprio(1); _Pragma("unroll") for (int m = 0; m < 4; ++m) _Pragma("unroll") for (int n = 0; n < 2; ++n) _Pragma("unroll") for (int k = 0; k < 2; ++k) \
;         acc[ai][bj][m][n] = __builtin_amdgcn_mfma_f32_16x16x32_bf16(Bt[n][k], At[m][k], acc[ai][bj][m][n], 0, 0, 0); __builtin_amdgcn_s_setprio(0); } while (0)
; #define PG8_WAIT_V(n) asm volatile("s_waitcnt vmcnt(" #n ")" ::: "memory")
; #define PG8_WAIT_L(n) asm volatile("s_waitcnt lgkmcnt(" #n ")" ::: "memory")
; #define PG8_BAR __builtin_amdgcn_s_barrier()
; #define PG8_SCHED __builtin_amdgcn_sched_barrier(0)
; template <class Epi, class Sched>
; __device__ __forceinline__ void gemm_phase(PG8_LAS unsigned char* lds, PG8_LAS unsigned char* xl, const Gemm g, const Sched& S, const Epi& E) {
;     ...
;             PG8_LDA(At, 0, 1); PG8_STAGE(PG8_SB(0, 0), b2, voffB); PG8_STAGE(PG8_SB(0, 1), b2 + hsB, voffB); PG8_STAGE(PG8_SA(0, 0), a2, voffA);
;             PG8_WAIT_V(8); PG8_WAIT_L(0); PG8_BAR; PG8_MMA(1, 0, At, B0); PG8_MMA(1, 1, At, B1); PG8_BAR; PG8_SCHED;
;             PG8_LDB(B0, 1, 0); PG8_LDB(B1, 1, 1); PG8_SCHED; PG8_LDA(At, 1, 0); PG8_STAGE(PG8_SA(0, 1), a2 + hsA, voffA);
;             PG8_WAIT_V(8); PG8_WAIT_L(0); PG8_BAR; PG8_MMA(0, 0, At, B0); PG8_MMA(0, 1, At, B1); PG8_BAR; PG8_SCHED;
	s_add_i32 s68, s54, s51
	v_lshl_add_u64 v[238:239], s[30:31], 0, v[132:133]
	s_mov_b32 m0, s68
	ds_read_b128 v[204:207], v166 offset:16384
	ds_read_b128 v[208:211], v166 offset:17408
	ds_read_b128 v[212:215], v166 offset:18432
	ds_read_b128 v[216:219], v166 offset:19456
	ds_read_b128 v[222:225], v166 offset:20480
	ds_read_b128 v[226:229], v166 offset:21504
	ds_read_b128 v[230:233], v166 offset:22528
	ds_read_b128 v[234:237], v166 offset:23552
	global_load_lds_dwordx4 v[238:239], off
	s_add_i32 m0, s68, 0x2000
	s_add_u32 s76, s30, 0x40000
	v_lshl_add_u64 v[240:241], s[30:31], 0, v[128:129]
	s_addc_u32 s77, s31, 0
	s_add_i32 s68, s62, s51
	global_load_lds_dwordx4 v[240:241], off
	v_lshl_add_u64 v[242:243], s[76:77], 0, v[132:133]
	s_mov_b32 m0, s68
	v_lshl_add_u64 v[244:245], s[34:35], 0, v[130:131]
	global_load_lds_dwordx4 v[242:243], off
	v_lshl_add_u64 v[242:243], s[76:77], 0, v[128:129]
	s_add_i32 m0, s68, 0x2000
	s_nop 0
	global_load_lds_dwordx4 v[242:243], off
	v_lshl_add_u64 v[242:243], s[34:35], 0, v[134:135]
	s_mov_b32 m0, s55
	s_nop 0
	global_load_lds_dwordx4 v[242:243], off
	s_mov_b32 m0, s56
	s_nop 0
	global_load_lds_dwordx4 v[244:245], off
	s_waitcnt vmcnt(8)
	s_waitcnt lgkmcnt(0)
	s_barrier
	s_setprio 1
	s_waitcnt lgkmcnt(0)
	v_mfma_f32_16x16x32_bf16 v[60:63], v[170:173], v[204:207], 0
	v_mfma_f32_16x16x32_bf16 v[52:55], v[180:183], v[204:207], 0
	v_mfma_f32_16x16x32_bf16 v[44:47], v[170:173], v[212:215], 0
	v_mfma_f32_16x16x32_bf16 v[36:39], v[180:183], v[212:215], 0
	v_mfma_f32_16x16x32_bf16 v[28:31], v[170:173], v[222:225], 0
	v_mfma_f32_16x16x32_bf16 v[20:23], v[180:183], v[222:225], 0
	v_mfma_f32_16x16x32_bf16 v[12:15], v[170:173], v[230:233], 0
	v_mfma_f32_16x16x32_bf16 v[4:7], v[180:183], v[230:233], 0
	v_mfma_f32_16x16x32_bf16 v[60:63], v[174:177], v[208:211], v[60:63]
	v_mfma_f32_16x16x32_bf16 v[52:55], v[184:187], v[208:211], v[52:55]
	v_mfma_f32_16x16x32_bf16 v[44:47], v[174:177], v[216:219], v[44:47]
	v_mfma_f32_16x16x32_bf16 v[36:39], v[184:187], v[216:219], v[36:39]
	v_mfma_f32_16x16x32_bf16 v[28:31], v[174:177], v[226:229], v[28:31]
	v_mfma_f32_16x16x32_bf16 v[20:23], v[184:187], v[226:229], v[20:23]
	v_mfma_f32_16x16x32_bf16 v[12:15], v[174:177], v[234:237], v[12:15]
	v_mfma_f32_16x16x32_bf16 v[4:7], v[184:187], v[234:237], v[4:7]
	s_setprio 0
	s_setprio 1
	v_mfma_f32_16x16x32_bf16 v[56:59], v[188:191], v[204:207], 0
	v_mfma_f32_16x16x32_bf16 v[48:51], v[196:199], v[204:207], 0
	v_mfma_f32_16x16x32_bf16 v[40:43], v[188:191], v[212:215], 0
	v_mfma_f32_16x16x32_bf16 v[32:35], v[196:199], v[212:215], 0
	v_mfma_f32_16x16x32_bf16 v[24:27], v[188:191], v[222:225], 0
	v_mfma_f32_16x16x32_bf16 v[16:19], v[196:199], v[222:225], 0
	v_mfma_f32_16x16x32_bf16 v[8:11], v[188:191], v[230:233], 0
	v_mfma_f32_16x16x32_bf16 v[0:3], v[196:199], v[230:233], 0
	v_mfma_f32_16x16x32_bf16 v[56:59], v[192:195], v[208:211], v[56:59]
	v_mfma_f32_16x16x32_bf16 v[48:51], v[200:203], v[208:211], v[48:51]
	v_mfma_f32_16x16x32_bf16 v[40:43], v[192:195], v[216:219], v[40:43]
	v_mfma_f32_16x16x32_bf16 v[32:35], v[200:203], v[216:219], v[32:35]
	v_mfma_f32_16x16x32_bf16 v[24:27], v[192:195], v[226:229], v[24:27]
	v_mfma_f32_16x16x32_bf16 v[16:19], v[200:203], v[226:229], v[16:19]
	v_mfma_f32_16x16x32_bf16 v[8:11], v[192:195], v[234:237], v[8:11]
	v_mfma_f32_16x16x32_bf16 v[0:3], v[200:203], v[234:237], v[0:3]
	s_setprio 0
	s_barrier
	s_add_i32 s68, 0, 0x18000
	v_add_u32_e32 v169, s68, v147
	s_add_i32 s76, 0, 0x1c000
	ds_read_b128 v[170:173], v169
	ds_read_b128 v[174:177], v169 offset:1024
	ds_read_b128 v[180:183], v169 offset:2048
	ds_read_b128 v[184:187], v169 offset:3072
	v_add_u32_e32 v169, s76, v147
	ds_read_b128 v[188:191], v169
	ds_read_b128 v[192:195], v169 offset:1024
	ds_read_b128 v[196:199], v169 offset:2048
	ds_read_b128 v[200:203], v169 offset:3072
	s_add_u32 s34, s34, 0x40000
	s_addc_u32 s35, s35, 0
	s_mov_b32 m0, s57
	v_lshl_add_u64 v[246:247], s[34:35], 0, v[134:135]
	ds_read_b128 v[204:207], v166 offset:32768
	ds_read_b128 v[208:211], v166 offset:33792
	ds_read_b128 v[212:215], v166 offset:34816
	ds_read_b128 v[216:219], v166 offset:35840
	ds_read_b128 v[222:225], v166 offset:36864
	ds_read_b128 v[226:229], v166 offset:37888
	ds_read_b128 v[230:233], v166 offset:38912
	ds_read_b128 v[234:237], v166 offset:39936
	global_load_lds_dwordx4 v[246:247], off
	v_lshl_add_u64 v[246:247], s[34:35], 0, v[130:131]
	s_mov_b32 m0, s58
	s_nop 0
	global_load_lds_dwordx4 v[246:247], off
	s_waitcnt vmcnt(8)
	s_waitcnt lgkmcnt(0)
	s_barrier
; #define PG8_STAGE(bufoff, gbase, voff) do { _Pragma("unroll") for (int _i = 0; _i < 2; ++_i) \
;         __builtin_amdgcn_global_load_lds((const unsigned*)((const char*)(gbase) + (voff)[_i]), (PG8_LAS unsigned*)(lds + (bufoff) + ldsw + _i * 8192), 16, 0, 0); } while (0)
; #define PG8_LDA(dst, b, h) do { _Pragma("unroll") for (int m = 0; m < 4; ++m) _Pragma("unroll") for (int k = 0; k < 2; ++k) dst[m][k] = *(const PG8_LAS bf16x8*)(lds + PG8_SA(b, h) + aoff + m * 2048 + k * 1024); } while (0)
; #define PG8_MMA(ai, bj, At, Bt) do { __builtin_amdgcn_s_setprio(1); _Pragma("unroll") for (int m = 0; m < 4; ++m) _Pragma("unroll") for (int n = 0; n < 2; ++n) _Pragma("unroll") for (int k = 0; k < 2; ++k) \
;         acc[ai][bj][m][n] = __builtin_amdgcn_mfma_f32_16x16x32_bf16(Bt[n][k], At[m][k], acc[ai][bj][m][n], 0, 0, 0); __builtin_amdgcn_s_setprio(0); } while (0)
; #define PG8_WAIT_V(n) asm volatile("s_waitcnt vmcnt(" #n ")" ::: "memory")
; #define PG8_WAIT_L(n) asm volatile("s_waitcnt lgkmcnt(" #n ")" ::: "memory")
; #define PG8_BAR __builtin_amdgcn_s_barrier()
; #define PG8_SCHED __builtin_amdgcn_sched_barrier(0)
; template <class Epi, class Sched>
; __device__ __forceinline__ void gemm_phase(PG8_LAS unsigned char* lds, PG8_LAS unsigned char* xl, const Gemm g, const Sched& S, const Epi& E) {
;     ...
;             PG8_WAIT_V(8); PG8_WAIT_L(0); PG8_BAR; PG8_MMA(0, 0, At, B0); PG8_MMA(0, 1, At, B1); PG8_BAR; PG8_SCHED;
;             PG8_LDA(At, 1, 1); PG8_STAGE(PG8_SB(1, 0), b3, voffB); PG8_STAGE(PG8_SB(1, 1), b3 + hsB, voffB); PG8_STAGE(PG8_SA(1, 0), a3, voffA);
;             PG8_WAIT_V(8); PG8_WAIT_L(0); PG8_BAR; PG8_MMA(1, 0, At, B0); PG8_MMA(1, 1, At, B1); PG8_BAR; PG8_SCHED;
;         }
	s_setprio 1
	s_waitcnt lgkmcnt(0)
	v_mfma_f32_16x16x32_bf16 v[124:127], v[170:173], v[204:207], v[124:127]
	v_mfma_f32_16x16x32_bf16 v[116:119], v[180:183], v[204:207], v[116:119]
	v_mfma_f32_16x16x32_bf16 v[108:111], v[170:173], v[212:215], v[108:111]
	v_mfma_f32_16x16x32_bf16 v[100:103], v[180:183], v[212:215], v[100:103]
	v_mfma_f32_16x16x32_bf16 v[92:95], v[170:173], v[222:225], v[92:95]
	v_mfma_f32_16x16x32_bf16 v[84:87], v[180:183], v[222:225], v[84:87]
	v_mfma_f32_16x16x32_bf16 v[76:79], v[170:173], v[230:233], v[76:79]
	v_mfma_f32_16x16x32_bf16 v[68:71], v[180:183], v[230:233], v[68:71]
	v_mfma_f32_16x16x32_bf16 v[124:127], v[174:177], v[208:211], v[124:127]
	v_mfma_f32_16x16x32_bf16 v[116:119], v[184:187], v[208:211], v[116:119]
	v_mfma_f32_16x16x32_bf16 v[108:111], v[174:177], v[216:219], v[108:111]
	v_mfma_f32_16x16x32_bf16 v[100:103], v[184:187], v[216:219], v[100:103]
	v_mfma_f32_16x16x32_bf16 v[92:95], v[174:177], v[226:229], v[92:95]
	v_mfma_f32_16x16x32_bf16 v[84:87], v[184:187], v[226:229], v[84:87]
	v_mfma_f32_16x16x32_bf16 v[76:79], v[174:177], v[234:237], v[76:79]
	v_mfma_f32_16x16x32_bf16 v[68:71], v[184:187], v[234:237], v[68:71]
	s_setprio 0
	s_setprio 1
	v_mfma_f32_16x16x32_bf16 v[120:123], v[188:191], v[204:207], v[120:123]
	v_mfma_f32_16x16x32_bf16 v[112:115], v[196:199], v[204:207], v[112:115]
	v_mfma_f32_16x16x32_bf16 v[104:107], v[188:191], v[212:215], v[104:107]
	v_mfma_f32_16x16x32_bf16 v[96:99], v[196:199], v[212:215], v[96:99]
	v_mfma_f32_16x16x32_bf16 v[88:91], v[188:191], v[222:225], v[88:91]
	v_mfma_f32_16x16x32_bf16 v[80:83], v[196:199], v[222:225], v[80:83]
	v_mfma_f32_16x16x32_bf16 v[72:75], v[188:191], v[230:233], v[72:75]
	v_mfma_f32_16x16x32_bf16 v[64:67], v[196:199], v[230:233], v[64:67]
	v_mfma_f32_16x16x32_bf16 v[120:123], v[192:195], v[208:211], v[120:123]
	v_mfma_f32_16x16x32_bf16 v[112:115], v[200:203], v[208:211], v[112:115]
	v_mfma_f32_16x16x32_bf16 v[104:107], v[192:195], v[216:219], v[104:107]
	v_mfma_f32_16x16x32_bf16 v[96:99], v[200:203], v[216:219], v[96:99]
	v_mfma_f32_16x16x32_bf16 v[88:91], v[192:195], v[226:229], v[88:91]
	v_mfma_f32_16x16x32_bf16 v[80:83], v[200:203], v[226:229], v[80:83]
	v_mfma_f32_16x16x32_bf16 v[72:75], v[192:195], v[234:237], v[72:75]
	v_mfma_f32_16x16x32_bf16 v[64:67], v[200:203], v[234:237], v[64:67]
	s_setprio 0
	s_barrier
	s_add_i32 s34, s68, s51
	v_lshl_add_u64 v[238:239], v[238:239], 0, s[16:17]
	s_mov_b32 m0, s34
	ds_read_b128 v[204:207], v166 offset:49152
	ds_read_b128 v[208:211], v166 offset:50176
	ds_read_b128 v[212:215], v166 offset:51200
	ds_read_b128 v[216:219], v166 offset:52224
	ds_read_b128 v[222:225], v166 offset:53248
	ds_read_b128 v[226:229], v166 offset:54272
	ds_read_b128 v[230:233], v166 offset:55296
	ds_read_b128 v[234:237], v166 offset:56320
	global_load_lds_dwordx4 v[238:239], off
	s_add_i32 m0, s34, 0x2000
	s_add_u32 s30, s30, 0x40080
	v_lshl_add_u64 v[238:239], v[240:241], 0, s[16:17]
	s_addc_u32 s31, s31, 0
	s_add_i32 s34, s76, s51
	global_load_lds_dwordx4 v[238:239], off
	v_lshl_add_u64 v[238:239], s[30:31], 0, v[132:133]
	s_mov_b32 m0, s34
	s_nop 0
	global_load_lds_dwordx4 v[238:239], off
	v_lshl_add_u64 v[238:239], s[30:31], 0, v[128:129]
	s_add_i32 m0, s34, 0x2000
	s_nop 0
	global_load_lds_dwordx4 v[238:239], off
	v_lshl_add_u64 v[238:239], v[242:243], 0, s[16:17]
	s_mov_b32 m0, s59
	s_nop 0
	global_load_lds_dwordx4 v[238:239], off
	v_lshl_add_u64 v[238:239], v[244:245], 0, s[16:17]
	s_mov_b32 m0, s61
	s_nop 0
	global_load_lds_dwordx4 v[238:239], off
	s_waitcnt vmcnt(8)
	s_waitcnt lgkmcnt(0)
	s_barrier
	s_setprio 1
	s_waitcnt lgkmcnt(0)
	v_mfma_f32_16x16x32_bf16 v[60:63], v[170:173], v[204:207], v[60:63]
	v_mfma_f32_16x16x32_bf16 v[52:55], v[180:183], v[204:207], v[52:55]
	v_mfma_f32_16x16x32_bf16 v[44:47], v[170:173], v[212:215], v[44:47]
	v_mfma_f32_16x16x32_bf16 v[36:39], v[180:183], v[212:215], v[36:39]
	v_mfma_f32_16x16x32_bf16 v[28:31], v[170:173], v[222:225], v[28:31]
	v_mfma_f32_16x16x32_bf16 v[20:23], v[180:183], v[222:225], v[20:23]
	v_mfma_f32_16x16x32_bf16 v[12:15], v[170:173], v[230:233], v[12:15]
	v_mfma_f32_16x16x32_bf16 v[4:7], v[180:183], v[230:233], v[4:7]
	v_mfma_f32_16x16x32_bf16 v[60:63], v[174:177], v[208:211], v[60:63]
	v_mfma_f32_16x16x32_bf16 v[52:55], v[184:187], v[208:211], v[52:55]
	v_mfma_f32_16x16x32_bf16 v[44:47], v[174:177], v[216:219], v[44:47]
	v_mfma_f32_16x16x32_bf16 v[36:39], v[184:187], v[216:219], v[36:39]
	v_mfma_f32_16x16x32_bf16 v[28:31], v[174:177], v[226:229], v[28:31]
	v_mfma_f32_16x16x32_bf16 v[20:23], v[184:187], v[226:229], v[20:23]
	v_mfma_f32_16x16x32_bf16 v[12:15], v[174:177], v[234:237], v[12:15]
	v_mfma_f32_16x16x32_bf16 v[4:7], v[184:187], v[234:237], v[4:7]
	s_setprio 0
	s_setprio 1
	v_mfma_f32_16x16x32_bf16 v[56:59], v[188:191], v[204:207], v[56:59]
	v_mfma_f32_16x16x32_bf16 v[48:51], v[196:199], v[204:207], v[48:51]
	v_mfma_f32_16x16x32_bf16 v[40:43], v[188:191], v[212:215], v[40:43]
	v_mfma_f32_16x16x32_bf16 v[32:35], v[196:199], v[212:215], v[32:35]
	v_mfma_f32_16x16x32_bf16 v[24:27], v[188:191], v[222:225], v[24:27]
	v_mfma_f32_16x16x32_bf16 v[16:19], v[196:199], v[222:225], v[16:19]
	v_mfma_f32_16x16x32_bf16 v[8:11], v[188:191], v[230:233], v[8:11]
	v_mfma_f32_16x16x32_bf16 v[0:3], v[196:199], v[230:233], v[0:3]
	v_mfma_f32_16x16x32_bf16 v[56:59], v[192:195], v[208:211], v[56:59]
	v_mfma_f32_16x16x32_bf16 v[48:51], v[200:203], v[208:211], v[48:51]
	v_mfma_f32_16x16x32_bf16 v[40:43], v[192:195], v[216:219], v[40:43]
	v_mfma_f32_16x16x32_bf16 v[32:35], v[200:203], v[216:219], v[32:35]
	v_mfma_f32_16x16x32_bf16 v[24:27], v[192:195], v[226:229], v[24:27]
	v_mfma_f32_16x16x32_bf16 v[16:19], v[200:203], v[226:229], v[16:19]
	v_mfma_f32_16x16x32_bf16 v[8:11], v[192:195], v[234:237], v[8:11]
	v_mfma_f32_16x16x32_bf16 v[0:3], v[200:203], v[234:237], v[0:3]
	s_setprio 0
	s_barrier
	s_add_i32 s75, s75, 2
	s_add_u32 s73, s73, 0x100
	s_addc_u32 s74, s74, 0
	s_add_u32 s2, s2, 0x100
	s_addc_u32 s3, s3, 0
	s_cmp_gt_u32 s75, 13
	s_cbranch_scc1 .Lpeel_after_P8
